# DIFF attention: first QK chain of each tile reads its four K fragments up front (counted lgkm waits), on top of MLA QK prefetch
# baseline (speedup 1.0000x reference)
.LBB0_1022:
	ds_read_b128 v[2:5], v193
	ds_read_b128 v[6:9], v193 offset:32
	ds_read_b128 v[228:231], v193 offset:64
	ds_read_b128 v[232:235], v193 offset:96
	s_waitcnt lgkmcnt(3)
	v_mfma_f32_32x32x16_bf16 v[80:95], v[2:5], v[96:99], 0
	s_waitcnt lgkmcnt(2)
	v_mfma_f32_32x32x16_bf16 v[80:95], v[6:9], v[100:103], v[80:95]
	s_waitcnt lgkmcnt(1)
	v_mfma_f32_32x32x16_bf16 v[80:95], v[228:231], v[104:107], v[80:95]
	s_waitcnt lgkmcnt(0)
	v_mfma_f32_32x32x16_bf16 v[80:95], v[232:235], v[108:111], v[80:95]
	s_nop 11
	v_max_f32_e32 v1, v81, v81
	v_max_f32_e32 v2, v80, v80
	v_max_f32_e32 v1, v2, v1
	v_max3_f32 v1, v1, v82, v83
	v_max3_f32 v1, v1, v84, v85
	v_max3_f32 v1, v1, v86, v87
	v_max3_f32 v1, v1, v88, v89
	v_max3_f32 v1, v1, v90, v91
	v_max3_f32 v1, v1, v92, v93
	v_max3_f32 v1, v1, v94, v95
	v_mov_b32_e32 v2, v1
	s_nop 1
	v_permlane32_swap_b32_e32 v2, v1
	s_waitcnt lgkmcnt(0)
	v_max_f32_e32 v2, v2, v2
	v_max_f32_e32 v1, v1, v2
	v_mul_f32_e32 v1, 0x3e38aa3b, v1
	v_add_f32_e32 v250, 0xc1000000, v1
	v_cmp_gt_f32_e32 vcc, v250, v180
	s_cbranch_vccz .LBB0_1024
	v_max_f32_e32 v1, v1, v1
	v_max_f32_e32 v2, v180, v180
	v_max_f32_e32 v1, v2, v1
	v_sub_f32_e32 v2, v180, v1
	v_exp_f32_e32 v2, v2
	v_mov_b32_e32 v180, v1
	v_pk_mul_f32 v[78:79], v[78:79], v[2:3] op_sel_hi:[1,0]
	v_pk_mul_f32 v[76:77], v[76:77], v[2:3] op_sel_hi:[1,0]
	v_pk_mul_f32 v[74:75], v[74:75], v[2:3] op_sel_hi:[1,0]
	v_pk_mul_f32 v[72:73], v[72:73], v[2:3] op_sel_hi:[1,0]
	v_pk_mul_f32 v[70:71], v[70:71], v[2:3] op_sel_hi:[1,0]
	v_pk_mul_f32 v[68:69], v[68:69], v[2:3] op_sel_hi:[1,0]
	v_pk_mul_f32 v[66:67], v[66:67], v[2:3] op_sel_hi:[1,0]
	v_pk_mul_f32 v[64:65], v[64:65], v[2:3] op_sel_hi:[1,0]
	v_pk_mul_f32 v[62:63], v[62:63], v[2:3] op_sel_hi:[1,0]
	v_pk_mul_f32 v[60:61], v[60:61], v[2:3] op_sel_hi:[1,0]
	v_pk_mul_f32 v[58:59], v[58:59], v[2:3] op_sel_hi:[1,0]
	v_pk_mul_f32 v[56:57], v[56:57], v[2:3] op_sel_hi:[1,0]
	v_pk_mul_f32 v[54:55], v[54:55], v[2:3] op_sel_hi:[1,0]
	v_pk_mul_f32 v[52:53], v[52:53], v[2:3] op_sel_hi:[1,0]
	v_pk_mul_f32 v[50:51], v[50:51], v[2:3] op_sel_hi:[1,0]
	v_pk_mul_f32 v[48:49], v[48:49], v[2:3] op_sel_hi:[1,0]
	v_pk_mul_f32 v[46:47], v[46:47], v[2:3] op_sel_hi:[1,0]
	v_pk_mul_f32 v[44:45], v[44:45], v[2:3] op_sel_hi:[1,0]
	v_pk_mul_f32 v[42:43], v[42:43], v[2:3] op_sel_hi:[1,0]
	v_pk_mul_f32 v[40:41], v[40:41], v[2:3] op_sel_hi:[1,0]
	v_pk_mul_f32 v[38:39], v[38:39], v[2:3] op_sel_hi:[1,0]
	v_pk_mul_f32 v[36:37], v[36:37], v[2:3] op_sel_hi:[1,0]
	v_pk_mul_f32 v[34:35], v[34:35], v[2:3] op_sel_hi:[1,0]
	v_pk_mul_f32 v[32:33], v[32:33], v[2:3] op_sel_hi:[1,0]
	v_pk_mul_f32 v[30:31], v[30:31], v[2:3] op_sel_hi:[1,0]
	v_pk_mul_f32 v[28:29], v[28:29], v[2:3] op_sel_hi:[1,0]
	v_pk_mul_f32 v[26:27], v[26:27], v[2:3] op_sel_hi:[1,0]
	v_pk_mul_f32 v[24:25], v[24:25], v[2:3] op_sel_hi:[1,0]
	v_pk_mul_f32 v[22:23], v[22:23], v[2:3] op_sel_hi:[1,0]
	v_pk_mul_f32 v[20:21], v[20:21], v[2:3] op_sel_hi:[1,0]
	v_pk_mul_f32 v[18:19], v[18:19], v[2:3] op_sel_hi:[1,0]
	v_pk_mul_f32 v[16:17], v[16:17], v[2:3] op_sel_hi:[1,0]
	v_mul_f32_e32 v196, v196, v2
